# norm1 modulation prologue: last partial-sum load issued before the wait (one round trip less per iteration), duplicate gain reload removed; otherwise v20
# baseline (speedup 1.0000x reference)
.LBB0_63:
	v_lshl_add_u64 v[2:3], s[34:35], 0, v[22:23]
	flat_load_dword v8, v[2:3]
	v_lshl_add_u64 v[2:3], s[26:27], 0, v[22:23]
	v_add_co_u32_e32 v4, vcc, 0x26c0000, v2
	s_nop 1
	v_addc_co_u32_e32 v5, vcc, 0, v3, vcc
	flat_load_dword v9, v[4:5]
	v_lshl_add_u64 v[4:5], s[30:31], 0, v[22:23]
	v_add_co_u32_e32 v6, vcc, 0x26f0000, v4
	s_nop 1
	v_addc_co_u32_e32 v7, vcc, 0, v5, vcc
	flat_load_dword v10, v[6:7]
	v_add_co_u32_e32 v6, vcc, 0x26f6000, v2
	s_nop 1
	v_addc_co_u32_e32 v7, vcc, 0, v3, vcc
	flat_load_dword v11, v[6:7]
	v_add_co_u32_e32 v6, vcc, 0x2726000, v4
	s_nop 1
	v_addc_co_u32_e32 v7, vcc, 0, v5, vcc
	flat_load_dword v12, v[6:7]
	v_add_co_u32_e32 v6, vcc, 0x272c000, v2
	s_nop 1
	v_addc_co_u32_e32 v7, vcc, 0, v3, vcc
	flat_load_dword v13, v[6:7]
	v_add_co_u32_e32 v6, vcc, 0x275c000, v4
	s_nop 1
	v_addc_co_u32_e32 v7, vcc, 0, v5, vcc
	flat_load_dword v14, v[6:7]
	v_add_co_u32_e32 v6, vcc, 0x2762000, v2
	s_nop 1
	v_addc_co_u32_e32 v7, vcc, 0, v3, vcc
	flat_load_dword v15, v[6:7]
	v_add_co_u32_e32 v6, vcc, 0x2792000, v4
	s_nop 1
	v_addc_co_u32_e32 v7, vcc, 0, v5, vcc
	flat_load_dword v18, v[6:7]
	v_add_co_u32_e32 v6, vcc, 0x2798000, v2
	s_nop 1
	v_addc_co_u32_e32 v7, vcc, 0, v3, vcc
	flat_load_dword v29, v[6:7]
	v_add_co_u32_e32 v6, vcc, 0x27c8000, v4
	s_nop 1
	v_addc_co_u32_e32 v7, vcc, 0, v5, vcc
	flat_load_dword v31, v[6:7]
	v_add_co_u32_e32 v6, vcc, 0x27ce000, v2
	s_nop 1
	v_addc_co_u32_e32 v7, vcc, 0, v3, vcc
	flat_load_dword v32, v[6:7]
	v_add_co_u32_e32 v6, vcc, 0x27fe000, v4
	s_nop 1
	v_addc_co_u32_e32 v7, vcc, 0, v5, vcc
	flat_load_dword v33, v[6:7]
	v_add_co_u32_e32 v6, vcc, 0x2804000, v2
	s_nop 1
	v_addc_co_u32_e32 v7, vcc, 0, v3, vcc
	flat_load_dword v43, v[6:7]
	v_add_co_u32_e32 v6, vcc, 0x2834000, v4
	s_nop 1
	v_addc_co_u32_e32 v7, vcc, 0, v5, vcc
	flat_load_dword v44, v[6:7]
	v_add_co_u32_e32 v6, vcc, 0x283a000, v2
	s_nop 1
	v_addc_co_u32_e32 v7, vcc, 0, v3, vcc
	flat_load_dword v45, v[6:7]
	v_add_co_u32_e32 v6, vcc, 0x286a000, v4
	s_nop 1
	v_addc_co_u32_e32 v7, vcc, 0, v5, vcc
	flat_load_dword v46, v[6:7]
	v_add_co_u32_e32 v6, vcc, 0x2870000, v2
	s_nop 1
	v_addc_co_u32_e32 v7, vcc, 0, v3, vcc
	flat_load_dword v47, v[6:7]
	v_add_co_u32_e32 v6, vcc, 0x28a0000, v4
	s_nop 1
	v_addc_co_u32_e32 v7, vcc, 0, v5, vcc
	flat_load_dword v48, v[6:7]
	v_add_co_u32_e32 v6, vcc, 0x28a6000, v2
	s_nop 1
	v_addc_co_u32_e32 v7, vcc, 0, v3, vcc
	flat_load_dword v49, v[6:7]
	v_add_co_u32_e32 v6, vcc, 0x28d6000, v4
	s_nop 1
	v_addc_co_u32_e32 v7, vcc, 0, v5, vcc
	flat_load_dword v50, v[6:7]
	v_add_co_u32_e32 v6, vcc, 0x28dc000, v2
	s_nop 1
	v_addc_co_u32_e32 v7, vcc, 0, v3, vcc
	flat_load_dword v51, v[6:7]
	v_add_co_u32_e32 v6, vcc, 0x290c000, v4
	s_nop 1
	v_addc_co_u32_e32 v7, vcc, 0, v5, vcc
	flat_load_dword v52, v[6:7]
	v_add_co_u32_e32 v6, vcc, 0x2912000, v2
	s_nop 1
	v_addc_co_u32_e32 v7, vcc, 0, v3, vcc
	flat_load_dword v53, v[6:7]
	v_add_co_u32_e32 v6, vcc, 0x2942000, v4
	s_nop 1
	v_addc_co_u32_e32 v7, vcc, 0, v5, vcc
	flat_load_dword v54, v[6:7]
	v_add_co_u32_e32 v6, vcc, 0x2948000, v2
	s_nop 1
	v_addc_co_u32_e32 v7, vcc, 0, v3, vcc
	flat_load_dword v55, v[6:7]
	v_add_co_u32_e32 v6, vcc, 0x2978000, v4
	s_nop 1
	v_addc_co_u32_e32 v7, vcc, 0, v5, vcc
	flat_load_dword v56, v[6:7]
	v_add_co_u32_e32 v6, vcc, 0x297e000, v2
	s_nop 1
	v_addc_co_u32_e32 v7, vcc, 0, v3, vcc
	flat_load_dword v57, v[6:7]
	v_add_co_u32_e32 v6, vcc, 0x29ae000, v4
	s_nop 1
	v_addc_co_u32_e32 v7, vcc, 0, v5, vcc
	flat_load_dword v58, v[6:7]
	v_add_co_u32_e32 v6, vcc, 0x29b4000, v2
	s_nop 1
	v_addc_co_u32_e32 v7, vcc, 0, v3, vcc
	flat_load_dword v59, v[6:7]
	v_add_co_u32_e32 v6, vcc, 0x29e4000, v4
	s_nop 1
	v_addc_co_u32_e32 v7, vcc, 0, v5, vcc
	v_add_co_u32_e32 v2, vcc, 0x29ea000, v2
	flat_load_dword v6, v[6:7]
	s_nop 0
	v_addc_co_u32_e32 v3, vcc, 0, v3, vcc
	flat_load_dword v7, v[2:3]
	v_add_co_u32_e32 v2, vcc, 0x2a1a000, v4
	s_nop 1
	v_addc_co_u32_e32 v3, vcc, 0, v5, vcc
	flat_load_dword v2, v[2:3]
	s_waitcnt vmcnt(0) lgkmcnt(0)
	v_add_f32_e32 v4, v8, v10
	v_add_f32_e32 v3, v8, v9
	v_add_f32_e32 v3, v3, v11
	v_add_f32_e32 v4, v4, v12
	v_add_f32_e32 v3, v3, v13
	v_add_f32_e32 v4, v4, v14
	v_add_f32_e32 v3, v3, v15
	v_add_f32_e32 v4, v4, v18
	v_add_f32_e32 v3, v3, v29
	v_add_f32_e32 v4, v4, v31
	v_add_f32_e32 v3, v3, v32
	v_add_f32_e32 v4, v4, v33
	v_add_f32_e32 v3, v3, v43
	v_add_f32_e32 v4, v4, v44
	v_add_f32_e32 v3, v3, v45
	v_add_f32_e32 v4, v4, v46
	v_add_f32_e32 v3, v3, v47
	v_add_f32_e32 v4, v4, v48
	v_add_f32_e32 v3, v3, v49
	v_add_f32_e32 v4, v4, v50
	v_add_f32_e32 v3, v3, v51
	v_add_f32_e32 v4, v4, v52
	v_cmp_lt_u32_e32 vcc, s3, v1
	v_add_f32_e32 v3, v3, v53
	v_add_f32_e32 v4, v4, v54
	v_add_f32_e32 v3, v3, v55
	v_add_f32_e32 v4, v4, v56
	v_add_f32_e32 v3, v3, v57
	v_add_f32_e32 v4, v4, v58
	v_add_f32_e32 v3, v3, v59
	v_add_f32_e32 v4, v4, v6
	v_add_f32_e32 v3, v3, v7
	s_waitcnt vmcnt(0) lgkmcnt(0)
	v_add_f32_e32 v2, v4, v2
	s_and_saveexec_b64 s[4:5], vcc
	s_xor_b64 s[36:37], exec, s[4:5]
	s_cbranch_execz .LBB0_65
	v_add_u32_e32 v18, 0xfffffc00, v1
	v_lshl_add_u64 v[4:5], v[18:19], 2, s[10:11]
	flat_load_dword v6, v[4:5]
	v_add_f32_e32 v3, 1.0, v3
	v_add_f32_e32 v2, 1.0, v2
	s_waitcnt vmcnt(0) lgkmcnt(0)
	v_mul_f32_e32 v3, v3, v6
	ds_write_b32 v0, v3
	v_mul_f32_e32 v2, v2, v6
	ds_write_b32 v0, v2 offset:8192
